# MLA second stream: batched K-fragment LDS reads for score block s0 (into the dead s1 accumulator registers) instead of one read-wait-MFMA at a time
# baseline (speedup 1.0000x reference)
; DI float fexp2(float x) { return __builtin_amdgcn_exp2f(x); }
; template <bool BOUND> ...
;     ...
;     if (BOUND) {
;       float ps = 0.f;
; #pragma unroll
;       for (int i = 0; i < 16; ++i) {
;         s0[i] = fexp2(s0[i]);
;         s1[i] = fexp2(s1[i]);
;         ps += s0[i] + s1[i];
;       }
;       l += ps;
;     } else {
;       float mx = fmaxf(s0[0], s1[0]);
; #pragma unroll
;       for (int i = 1; i < 16; ++i) mx = fmaxf(mx, fmaxf(s0[i], s1[i]));
;       mx = fmaxf(mx, xhalf(mx));
;       const float mnew = fmaxf(m, mx);
;       const float alpha = fexp2(m - mnew);
;       m = mnew;
;       float ps = 0.f;
; #pragma unroll
;       for (int i = 0; i < 16; ++i) {
;         s0[i] = fexp2(s0[i] - mnew);
;         s1[i] = fexp2(s1[i] - mnew);
;         ps += s0[i] + s1[i];
;       }
;       l = l * alpha + ps;
; #pragma unroll
;       for (int i = 0; i < 16; ++i) { o0[i] *= alpha; o1[i] *= alpha; }
;     }
;     const char* vb0 = cur + A_VOFF + r * V_ROW + hf * 128 + 16 * h;
; #pragma unroll
;     for (int kb = 0; kb < 2; ++kb)
; #pragma unroll
;       for (int s = 0; s < 2; ++s) {
;         uint4 pu;
;         if (kb == 0) {
;           pu.x = pk_bf16(s0[8 * s + 0], s0[8 * s + 1]); pu.y = pk_bf16(s0[8 * s + 2], s0[8 * s + 3]);
;           pu.z = pk_bf16(s0[8 * s + 4], s0[8 * s + 5]); pu.w = pk_bf16(s0[8 * s + 6], s0[8 * s + 7]);
;         } else {
;           pu.x = pk_bf16(s1[8 * s + 0], s1[8 * s + 1]); pu.y = pk_bf16(s1[8 * s + 2], s1[8 * s + 3]);
;     ...
;       for (int st = 0; st < 2; ++st) {
;         __builtin_amdgcn_sched_barrier(0);
; #pragma unroll
;         for (int i = 0; i < 16; ++i) { s0[i] = 0.f; s1[i] = 0.f; }
; #pragma unroll
;         for (int c = 0; c < 3; ++c) {
;           bf16x8 ka[2], kb[2];
; #pragma unroll
;           for (int ks = 0; ks < 2; ++ks) {
;             ka[ks] = *(const bf16x8*)(kb0 + c * 64 + ks * 32);
;             kb[ks] = *(const bf16x8*)(kb0 + 32 * KSTR + c * 64 + ks * 32);
;           }
; #pragma unroll
;           for (int ks = 0; ks < 2; ++ks) {
;             if (st == 0) { s0 = MFMA(ka[ks], qa[c][ks], s0); s1 = MFMA(kb[ks], qa[c][ks], s1); }
;             else         { s0 = MFMA(ka[ks], qb[c][ks], s0); s1 = MFMA(kb[ks], qb[c][ks], s1); }
;           }
;         }
;         if (st == 0) softmax_pv(cur, hf, s0, s1, mA, lA, oA0, oA1);
;         else         softmax_pv(cur, hf, s0, s1, mB, lB, oB0, oB1);
.LBB0_374:
	v_lshl_or_b32 v66, s31, 6, v243
	s_xor_b64 s[2:3], s[8:9], -1
	v_mad_u32_u24 v167, v66, s37, v185
	v_lshl_add_u32 v247, s31, 7, v246
	ds_read_b128 v[66:69], v167
	ds_read_b128 v[192:195], v167 offset:32
	s_waitcnt lgkmcnt(1)
	v_mfma_f32_32x32x16_bf16 v[82:97], v[66:69], v[118:121], 0
	ds_read_b128 v[66:69], v167 offset:6656
	ds_read_b128 v[196:199], v167 offset:6688
	s_waitcnt lgkmcnt(1)
	v_mfma_f32_32x32x16_bf16 v[66:81], v[66:69], v[118:121], 0
	v_mfma_f32_32x32x16_bf16 v[82:97], v[192:195], v[126:129], v[82:97]
	s_waitcnt lgkmcnt(0)
	v_mfma_f32_32x32x16_bf16 v[66:81], v[196:199], v[126:129], v[66:81]
	ds_read_b128 v[192:195], v167 offset:64
	ds_read_b128 v[196:199], v167 offset:96
	s_waitcnt lgkmcnt(1)
	v_mfma_f32_32x32x16_bf16 v[82:97], v[192:195], v[134:137], v[82:97]
	ds_read_b128 v[192:195], v167 offset:6720
	ds_read_b128 v[200:203], v167 offset:6752
	s_waitcnt lgkmcnt(1)
	v_mfma_f32_32x32x16_bf16 v[66:81], v[192:195], v[134:137], v[66:81]
	v_mfma_f32_32x32x16_bf16 v[82:97], v[196:199], v[142:145], v[82:97]
	ds_read_b128 v[192:195], v167 offset:128
	ds_read_b128 v[196:199], v167 offset:160
	s_waitcnt lgkmcnt(2)
	v_mfma_f32_32x32x16_bf16 v[66:81], v[200:203], v[142:145], v[66:81]
	s_waitcnt lgkmcnt(1)
	v_mfma_f32_32x32x16_bf16 v[82:97], v[192:195], v[150:153], v[82:97]
	ds_read_b128 v[192:195], v167 offset:6784
	ds_read_b128 v[200:203], v167 offset:6816
	s_waitcnt lgkmcnt(1)
	v_mfma_f32_32x32x16_bf16 v[66:81], v[192:195], v[150:153], v[66:81]
	v_mfma_f32_32x32x16_bf16 v[82:97], v[196:199], v[158:161], v[82:97]
	s_waitcnt lgkmcnt(0)
	v_mfma_f32_32x32x16_bf16 v[66:81], v[200:203], v[158:161], v[66:81]
	s_nop 9
	v_exp_f32_e32 v166, v82
	v_exp_f32_e32 v203, v84
	v_exp_f32_e32 v205, v85
	v_exp_f32_e32 v207, v86
	v_exp_f32_e32 v209, v87
	v_exp_f32_e32 v215, v88
	v_exp_f32_e32 v204, v89
	v_exp_f32_e32 v193, v66
	v_exp_f32_e32 v66, v83
	ds_read_b128 v[82:85], v247 offset:26624
	ds_read_b128 v[210:213], v247 offset:26656
	ds_read_b128 v[196:199], v247 offset:35328
	v_cvt_pk_bf16_f32 v87, v203, v205
	v_cvt_pk_bf16_f32 v86, v166, v66
	v_cvt_pk_bf16_f32 v88, v207, v209
	v_cvt_pk_bf16_f32 v89, v215, v204
	v_exp_f32_e32 v195, v67
	v_exp_f32_e32 v208, v90
	s_waitcnt lgkmcnt(2)
	v_mfma_f32_32x32x16_bf16 v[34:49], v[82:85], v[86:89], v[34:49]
	ds_read_b128 v[82:85], v247 offset:35360
	v_exp_f32_e32 v206, v91
	v_exp_f32_e32 v202, v92
	v_exp_f32_e32 v194, v93
	v_exp_f32_e32 v192, v94
	v_exp_f32_e32 v200, v95
	v_add_f32_e32 v67, v166, v193
	s_waitcnt lgkmcnt(1)
	v_mfma_f32_32x32x16_bf16 v[2:17], v[196:199], v[86:89], v[2:17]
	v_exp_f32_e32 v198, v96
	v_exp_f32_e32 v196, v97
	v_add_f32_e32 v67, 0, v67
	v_add_f32_e32 v201, v66, v195
	v_exp_f32_e32 v166, v68
	v_cvt_pk_bf16_f32 v86, v208, v206
	v_cvt_pk_bf16_f32 v87, v202, v194
	v_cvt_pk_bf16_f32 v88, v192, v200
	v_cvt_pk_bf16_f32 v89, v198, v196
	v_add_f32_e32 v90, v201, v67
	v_exp_f32_e32 v92, v69
	ds_read_b128 v[66:69], v247 offset:26688
	v_mfma_f32_32x32x16_bf16 v[34:49], v[210:213], v[86:89], v[34:49]
	v_exp_f32_e32 v93, v70
	v_exp_f32_e32 v94, v71
	v_exp_f32_e32 v95, v72
	v_exp_f32_e32 v226, v73
	v_cvt_pk_bf16_f32 v70, v193, v195
	v_cvt_pk_bf16_f32 v71, v166, v92
	v_cvt_pk_bf16_f32 v72, v93, v94
	s_waitcnt lgkmcnt(1)
	v_mfma_f32_32x32x16_bf16 v[2:17], v[82:85], v[86:89], v[2:17]
	ds_read_b128 v[82:85], v247 offset:35392
	ds_read_b128 v[86:89], v247 offset:26720
	v_cvt_pk_bf16_f32 v73, v95, v226
	v_exp_f32_e32 v210, v74
	v_exp_f32_e32 v214, v75
	v_exp_f32_e32 v212, v76
	v_exp_f32_e32 v218, v77
	v_exp_f32_e32 v216, v78
	s_waitcnt lgkmcnt(2)
	v_mfma_f32_32x32x16_bf16 v[34:49], v[66:69], v[70:73], v[34:49]
	ds_read_b128 v[66:69], v247 offset:35424
	v_exp_f32_e32 v224, v79
	v_exp_f32_e32 v222, v80
	v_exp_f32_e32 v220, v81
	v_add_f32_e32 v91, v203, v166
	v_add_f32_e32 v90, v91, v90
	v_add_f32_e32 v74, v205, v92
	s_waitcnt lgkmcnt(2)
	v_mfma_f32_32x32x16_bf16 v[2:17], v[82:85], v[70:73], v[2:17]
	v_cvt_pk_bf16_f32 v70, v210, v214
	v_cvt_pk_bf16_f32 v71, v212, v218
	v_cvt_pk_bf16_f32 v72, v216, v224
	v_cvt_pk_bf16_f32 v73, v222, v220
	v_add_f32_e32 v74, v74, v90
	v_add_f32_e32 v75, v207, v93
	v_add_f32_e32 v74, v75, v74
	s_waitcnt lgkmcnt(1)
	v_mfma_f32_32x32x16_bf16 v[34:49], v[86:89], v[70:73], v[34:49]
	v_add_f32_e32 v75, v209, v94
	v_add_f32_e32 v248, v75, v74
	v_add_f32_e32 v166, v215, v95
	s_waitcnt lgkmcnt(0)
	v_mfma_f32_32x32x16_bf16 v[2:17], v[66:69], v[70:73], v[2:17]
	ds_read_b128 v[66:69], v167
	ds_read_b128 v[82:85], v167 offset:32
	ds_read_b128 v[86:89], v167 offset:64
	ds_read_b128 v[90:93], v167 offset:96
	ds_read_b128 v[94:97], v167 offset:128
	ds_read_b128 v[236:239], v167 offset:160
	s_mov_b32 s31, 1
	s_mov_b64 s[8:9], 0
	s_mov_b64 s[28:29], -1
	s_and_b64 vcc, exec, s[2:3]
	s_waitcnt lgkmcnt(5)
	v_mfma_f32_32x32x16_bf16 v[66:81], v[66:69], v[122:125], 0
	s_waitcnt lgkmcnt(4)
	v_mfma_f32_32x32x16_bf16 v[66:81], v[82:85], v[130:133], v[66:81]
	s_waitcnt lgkmcnt(3)
; #define MFMA(a, b, c) __builtin_amdgcn_mfma_f32_32x32x16_bf16((a), (b), (c), 0, 0, 0)
; template <bool BOUND> ...
;     ...
;     if (BOUND) {
;       float ps = 0.f;
; #pragma unroll
;       for (int i = 0; i < 16; ++i) {
;         s0[i] = fexp2(s0[i]);
;         s1[i] = fexp2(s1[i]);
;         ps += s0[i] + s1[i];
;       }
;       l += ps;
;     } else {
;       float mx = fmaxf(s0[0], s1[0]);
; #pragma unroll
;       for (int i = 1; i < 16; ++i) mx = fmaxf(mx, fmaxf(s0[i], s1[i]));
;       mx = fmaxf(mx, xhalf(mx));
;       const float mnew = fmaxf(m, mx);
;       const float alpha = fexp2(m - mnew);
;       m = mnew;
;       float ps = 0.f;
; #pragma unroll
;       for (int i = 0; i < 16; ++i) {
;         s0[i] = fexp2(s0[i] - mnew);
;         s1[i] = fexp2(s1[i] - mnew);
;         ps += s0[i] + s1[i];
;       }
;       l = l * alpha + ps;
; #pragma unroll
;       for (int i = 0; i < 16; ++i) { o0[i] *= alpha; o1[i] *= alpha; }
;     }
;     const char* vb0 = cur + A_VOFF + r * V_ROW + hf * 128 + 16 * h;
; #pragma unroll
;     for (int kb = 0; kb < 2; ++kb)
; #pragma unroll
;       for (int s = 0; s < 2; ++s) {
;         uint4 pu;
;         if (kb == 0) {
;           pu.x = pk_bf16(s0[8 * s + 0], s0[8 * s + 1]); pu.y = pk_bf16(s0[8 * s + 2], s0[8 * s + 3]);
;           pu.z = pk_bf16(s0[8 * s + 4], s0[8 * s + 5]); pu.w = pk_bf16(s0[8 * s + 6], s0[8 * s + 7]);
;         } else {
;           pu.x = pk_bf16(s1[8 * s + 0], s1[8 * s + 1]); pu.y = pk_bf16(s1[8 * s + 2], s1[8 * s + 3]);
;           pu.z = pk_bf16(s1[8 * s + 4], s1[8 * s + 5]); pu.w = pk_bf16(s1[8 * s + 6], s1[8 * s + 7]);
;         }
;         const bf16x8 pf = __builtin_bit_cast(bf16x8, pu);
;         const int koff = (kb * 32 + 16 * s) * 2;
;         { const bf16x8 vf = *(const bf16x8*)(vb0 + koff); o0 = MFMA(vf, pf, o0); }
;     ...
;         for (int c = 0; c < 3; ++c) {
;           bf16x8 ka[2], kb[2];
; #pragma unroll
;           for (int ks = 0; ks < 2; ++ks) {
;             ka[ks] = *(const bf16x8*)(kb0 + c * 64 + ks * 32);
;             kb[ks] = *(const bf16x8*)(kb0 + 32 * KSTR + c * 64 + ks * 32);
;           }
; #pragma unroll
;           for (int ks = 0; ks < 2; ++ks) {
;             if (st == 0) { s0 = MFMA(ka[ks], qa[c][ks], s0); s1 = MFMA(kb[ks], qa[c][ks], s1); }
;             else         { s0 = MFMA(ka[ks], qb[c][ks], s0); s1 = MFMA(kb[ks], qb[c][ks], s1); }
;           }
;         }
	v_mfma_f32_32x32x16_bf16 v[66:81], v[86:89], v[138:141], v[66:81]
	s_waitcnt lgkmcnt(2)
	v_mfma_f32_32x32x16_bf16 v[66:81], v[90:93], v[146:149], v[66:81]
	s_waitcnt lgkmcnt(1)
	v_mfma_f32_32x32x16_bf16 v[66:81], v[94:97], v[154:157], v[66:81]
	s_waitcnt lgkmcnt(0)
	v_mfma_f32_32x32x16_bf16 v[66:81], v[236:239], v[162:165], v[66:81]
	ds_read_b128 v[82:85], v167 offset:6656
	ds_read_b128 v[236:239], v167 offset:6688
	s_waitcnt lgkmcnt(1)
	v_mfma_f32_32x32x16_bf16 v[82:97], v[82:85], v[122:125], 0
	s_waitcnt lgkmcnt(0)
	v_mfma_f32_32x32x16_bf16 v[82:97], v[236:239], v[130:133], v[82:97]
	ds_read_b128 v[236:239], v167 offset:6720
	s_waitcnt lgkmcnt(0)
	v_mfma_f32_32x32x16_bf16 v[82:97], v[236:239], v[138:141], v[82:97]
	ds_read_b128 v[236:239], v167 offset:6752
	s_waitcnt lgkmcnt(0)
	v_mfma_f32_32x32x16_bf16 v[82:97], v[236:239], v[146:149], v[82:97]
	ds_read_b128 v[236:239], v167 offset:6784
	s_waitcnt lgkmcnt(0)
	v_mfma_f32_32x32x16_bf16 v[82:97], v[236:239], v[154:157], v[82:97]
	ds_read_b128 v[236:239], v167 offset:6816
	s_waitcnt lgkmcnt(0)
	v_mfma_f32_32x32x16_bf16 v[82:97], v[236:239], v[162:165], v[82:97]
	s_nop 8
	v_exp_f32_e32 v193, v66
	v_exp_f32_e32 v197, v71
	v_exp_f32_e32 v199, v72
	v_exp_f32_e32 v205, v73
	v_exp_f32_e32 v209, v74
	v_exp_f32_e32 v207, v75
	v_exp_f32_e32 v203, v76
	v_exp_f32_e32 v236, v82
	v_exp_f32_e32 v82, v67
	v_exp_f32_e32 v237, v83
	v_exp_f32_e32 v83, v68
	v_exp_f32_e32 v238, v84
	v_exp_f32_e32 v84, v69
	v_exp_f32_e32 v239, v85
	v_add_f32_e32 v66, v193, v236
	v_exp_f32_e32 v85, v70
	v_exp_f32_e32 v86, v86
	v_add_f32_e32 v66, 0, v66
	v_add_f32_e32 v67, v82, v237
	v_exp_f32_e32 v87, v87
	v_add_f32_e32 v66, v67, v66
	v_add_f32_e32 v67, v83, v238
	v_add_f32_e32 v66, v67, v66
	v_add_f32_e32 v67, v84, v239
	v_add_f32_e32 v66, v67, v66
	v_add_f32_e32 v67, v85, v86
	v_add_f32_e32 v66, v67, v66
	v_add_f32_e32 v67, v197, v87
	v_add_f32_e32 v249, v67, v66
	ds_read_b128 v[66:69], v247 offset:26624
	v_exp_f32_e32 v88, v88
	v_cvt_pk_bf16_f32 v70, v193, v82
	v_cvt_pk_bf16_f32 v71, v83, v84
	v_cvt_pk_bf16_f32 v72, v85, v197
	v_cvt_pk_bf16_f32 v73, v199, v205
	v_exp_f32_e32 v195, v77
	ds_read_b128 v[74:77], v247 offset:26656
	ds_read_b128 v[82:85], v247 offset:35328
	s_waitcnt lgkmcnt(2)
	v_mfma_f32_32x32x16_bf16 v[50:65], v[66:69], v[70:73], v[50:65]
	v_add_f32_e32 v167, v199, v88
	v_exp_f32_e32 v193, v78
	v_exp_f32_e32 v201, v79
	v_exp_f32_e32 v199, v80
	v_exp_f32_e32 v197, v81
	v_exp_f32_e32 v227, v89
	v_exp_f32_e32 v211, v90
	v_exp_f32_e32 v215, v91
	ds_read_b128 v[66:69], v247 offset:35360
	s_waitcnt lgkmcnt(1)
	v_mfma_f32_32x32x16_bf16 v[18:33], v[82:85], v[70:73], v[18:33]
	v_cvt_pk_bf16_f32 v70, v209, v207
	v_cvt_pk_bf16_f32 v71, v203, v195
	v_cvt_pk_bf16_f32 v72, v193, v201
	v_cvt_pk_bf16_f32 v73, v199, v197
	v_add_f32_e64 v78, v166, v248
	v_add_f32_e64 v79, v167, v249
	v_exp_f32_e32 v213, v92
	v_exp_f32_e32 v219, v93
	v_mfma_f32_32x32x16_bf16 v[50:65], v[74:77], v[70:73], v[50:65]
	v_add_f32_e64 v74, v204, v226
	v_add_f32_e64 v75, v205, v227
	v_add_f32_e64 v76, v208, v210
	v_add_f32_e64 v77, v209, v211
	v_add_f32_e64 v74, v74, v78
	v_add_f32_e64 v75, v75, v79
	v_exp_f32_e32 v217, v94
	v_pk_add_f32 v[74:75], v[76:77], v[74:75]
	v_pk_add_f32 v[76:77], v[206:207], v[214:215]
	v_pk_add_f32 v[84:85], v[202:203], v[212:213]
	v_pk_add_f32 v[82:83], v[76:77], v[74:75]
	ds_read_b128 v[74:77], v247 offset:26688
	s_waitcnt lgkmcnt(1)
	v_mfma_f32_32x32x16_bf16 v[18:33], v[66:69], v[70:73], v[18:33]
	v_cvt_pk_bf16_f32 v66, v236, v237
	v_cvt_pk_bf16_f32 v67, v238, v239
	v_cvt_pk_bf16_f32 v68, v86, v87
	v_cvt_pk_bf16_f32 v69, v88, v227
	ds_read_b128 v[70:73], v247 offset:35392
	ds_read_b128 v[78:81], v247 offset:26720
	v_exp_f32_e32 v225, v95
	v_exp_f32_e32 v223, v96
	s_waitcnt lgkmcnt(2)
	v_mfma_f32_32x32x16_bf16 v[50:65], v[74:77], v[66:69], v[50:65]
	v_add_f32_e64 v74, v84, v82
	v_add_f32_e64 v75, v85, v83
	v_add_f32_e64 v76, v194, v218
	v_add_f32_e64 v77, v195, v219
	v_exp_f32_e32 v221, v97
	v_pk_add_f32 v[74:75], v[76:77], v[74:75]
	v_pk_add_f32 v[76:77], v[192:193], v[216:217]
	v_pk_add_f32 v[84:85], v[200:201], v[224:225]
	v_pk_add_f32 v[82:83], v[76:77], v[74:75]
	ds_read_b128 v[74:77], v247 offset:35424
	s_waitcnt lgkmcnt(2)
	v_mfma_f32_32x32x16_bf16 v[18:33], v[70:73], v[66:69], v[18:33]
	v_add_f32_e64 v66, v84, v82
	v_add_f32_e64 v67, v85, v83
	v_add_f32_e64 v68, v198, v222
	v_add_f32_e64 v69, v199, v223
	v_add_f32_e64 v72, v196, v220
	v_add_f32_e64 v73, v197, v221
	v_pk_add_f32 v[70:71], v[68:69], v[66:67]
	v_cvt_pk_bf16_f32 v66, v211, v215
	v_cvt_pk_bf16_f32 v67, v213, v219
	v_cvt_pk_bf16_f32 v68, v217, v225
	v_cvt_pk_bf16_f32 v69, v223, v221
	v_pk_add_f32 v[70:71], v[72:73], v[70:71]
	s_waitcnt lgkmcnt(1)
	v_mfma_f32_32x32x16_bf16 v[50:65], v[78:81], v[66:69], v[50:65]
	v_add_f32_e64 v182, v182, v70
	v_add_f32_e64 v183, v183, v71
	s_waitcnt lgkmcnt(0)
	v_mfma_f32_32x32x16_bf16 v[18:33], v[74:77], v[66:69], v[18:33]
	s_cbranch_vccnz .LBB0_377
